# removed the loop-preheader vmcnt(0) drains before the GEMM k-loops (P3,P4,P7,P8,P9)
# speedup vs baseline: 1.0038x; 1.0038x over previous
; template <class Epi, class Sched>
; __device__ __forceinline__ void gemm_phase(PG8_LAS unsigned char* lds, PG8_LAS unsigned char* xl, const Gemm g, const Sched& S, const Epi& E) {
;     ...
;         const bool has_next = S.next(ui + 1, nxt);
;         const char* nA = has_next ? (const char*)g.A + nxt.aoff : cA; const char* nB = has_next ? (const char*)g.Bt + nxt.boff : cB;
;     ...
; #pragma unroll
;         for (int a = 0; a < 2; ++a)
; #pragma unroll
;             for (int b = 0; b < 2; ++b)
; #pragma unroll
;                 for (int m = 0; m < 4; ++m)
; #pragma unroll
;                     for (int n = 0; n < 2; ++n) acc[a][b][m][n] = (f32x4){0.f, 0.f, 0.f, 0.f};
.LBB0_470:
	s_add_u32 s26, s43, s20
	s_addc_u32 s27, s50, s21
	s_and_b64 s[28:29], s[8:9], exec
	s_cselect_b32 s33, s27, s35
	s_cselect_b32 s46, s26, s34
	s_add_u32 s28, s51, s22
	s_addc_u32 s29, s52, s23
	s_and_b64 s[36:37], s[8:9], exec
	s_cselect_b32 s47, s29, s31
	s_cselect_b32 s70, s28, s30
	s_add_u32 s72, s30, 0x100
	s_addc_u32 s73, s31, 0
	s_add_u32 s30, s34, 0x40080
	v_mov_b32_e32 v0, 0
	s_addc_u32 s31, s35, 0
	s_mov_b32 s74, -2
	s_waitcnt lgkmcnt(0)
	v_mov_b32_e32 v1, v0
	v_mov_b32_e32 v2, v0
	v_mov_b32_e32 v3, v0
	v_mov_b32_e32 v4, v0
	v_mov_b32_e32 v5, v0
	v_mov_b32_e32 v6, v0
	v_mov_b32_e32 v7, v0
	v_mov_b32_e32 v16, v0
	v_mov_b32_e32 v17, v0
	v_mov_b32_e32 v18, v0
	v_mov_b32_e32 v19, v0
	v_mov_b32_e32 v20, v0
	v_mov_b32_e32 v21, v0
	v_mov_b32_e32 v22, v0
	v_mov_b32_e32 v23, v0
	v_mov_b32_e32 v32, v0
	v_mov_b32_e32 v33, v0
	v_mov_b32_e32 v34, v0
	v_mov_b32_e32 v35, v0
	v_mov_b32_e32 v36, v0
	v_mov_b32_e32 v37, v0
	v_mov_b32_e32 v38, v0
	v_mov_b32_e32 v39, v0
	v_mov_b32_e32 v48, v0
	v_mov_b32_e32 v49, v0
	v_mov_b32_e32 v50, v0
	v_mov_b32_e32 v51, v0
	v_mov_b32_e32 v52, v0
	v_mov_b32_e32 v53, v0
	v_mov_b32_e32 v54, v0
	v_mov_b32_e32 v55, v0
	v_mov_b32_e32 v8, v0
	v_mov_b32_e32 v9, v0
	v_mov_b32_e32 v10, v0
	v_mov_b32_e32 v11, v0
	v_mov_b32_e32 v12, v0
	v_mov_b32_e32 v13, v0
	v_mov_b32_e32 v14, v0
	v_mov_b32_e32 v15, v0
	v_mov_b32_e32 v24, v0
	v_mov_b32_e32 v25, v0
	v_mov_b32_e32 v26, v0
	v_mov_b32_e32 v27, v0
	v_mov_b32_e32 v28, v0
	v_mov_b32_e32 v29, v0
	v_mov_b32_e32 v30, v0
	v_mov_b32_e32 v31, v0
	v_mov_b32_e32 v40, v0
	v_mov_b32_e32 v41, v0
	v_mov_b32_e32 v42, v0
	v_mov_b32_e32 v43, v0
	v_mov_b32_e32 v44, v0
	v_mov_b32_e32 v45, v0
	v_mov_b32_e32 v46, v0
	v_mov_b32_e32 v47, v0
	v_mov_b32_e32 v56, v0
	v_mov_b32_e32 v57, v0
	v_mov_b32_e32 v58, v0
	v_mov_b32_e32 v59, v0
	v_mov_b32_e32 v60, v0
	v_mov_b32_e32 v61, v0
	v_mov_b32_e32 v62, v0
	v_mov_b32_e32 v63, v0
	v_mov_b32_e32 v64, v0
	v_mov_b32_e32 v65, v0
	v_mov_b32_e32 v66, v0
	v_mov_b32_e32 v67, v0
	v_mov_b32_e32 v68, v0
	v_mov_b32_e32 v69, v0
	v_mov_b32_e32 v70, v0
	v_mov_b32_e32 v71, v0
	v_mov_b32_e32 v80, v0
	v_mov_b32_e32 v81, v0
	v_mov_b32_e32 v82, v0
	v_mov_b32_e32 v83, v0
	v_mov_b32_e32 v84, v0
	v_mov_b32_e32 v85, v0
	v_mov_b32_e32 v86, v0
	v_mov_b32_e32 v87, v0
	v_mov_b32_e32 v96, v0
	v_mov_b32_e32 v97, v0
	v_mov_b32_e32 v98, v0
	v_mov_b32_e32 v99, v0
	s_nop 0
	v_mov_b32_e32 v100, v0
	v_mov_b32_e32 v101, v0
	v_mov_b32_e32 v102, v0
	v_mov_b32_e32 v103, v0
	v_mov_b32_e32 v112, v0
	v_mov_b32_e32 v113, v0
	v_mov_b32_e32 v114, v0
	v_mov_b32_e32 v115, v0
	v_mov_b32_e32 v116, v0
	v_mov_b32_e32 v117, v0
	v_mov_b32_e32 v118, v0
	v_mov_b32_e32 v119, v0
	v_mov_b32_e32 v72, v0
	v_mov_b32_e32 v73, v0
	v_mov_b32_e32 v74, v0
	v_mov_b32_e32 v75, v0
	v_mov_b32_e32 v76, v0
	v_mov_b32_e32 v77, v0
	v_mov_b32_e32 v78, v0
	v_mov_b32_e32 v79, v0
	v_mov_b32_e32 v88, v0
	v_mov_b32_e32 v89, v0
	v_mov_b32_e32 v90, v0
	v_mov_b32_e32 v91, v0
	v_mov_b32_e32 v92, v0
	v_mov_b32_e32 v93, v0
	v_mov_b32_e32 v94, v0
	v_mov_b32_e32 v95, v0
	v_mov_b32_e32 v104, v0
	v_mov_b32_e32 v105, v0
	v_mov_b32_e32 v106, v0
	v_mov_b32_e32 v107, v0
	v_mov_b32_e32 v108, v0
	v_mov_b32_e32 v109, v0
	v_mov_b32_e32 v110, v0
	v_mov_b32_e32 v111, v0
	v_mov_b32_e32 v120, v0
	v_mov_b32_e32 v121, v0
	v_mov_b32_e32 v122, v0
	v_mov_b32_e32 v123, v0
	v_mov_b32_e32 v124, v0
	v_mov_b32_e32 v125, v0
	v_mov_b32_e32 v126, v0
	v_mov_b32_e32 v127, v0

; template <class Epi, class Sched>
; __device__ __forceinline__ void gemm_phase(PG8_LAS unsigned char* lds, PG8_LAS unsigned char* xl, const Gemm g, const Sched& S, const Epi& E) {
;     ...
;         const bool has_next = S.next(ui + 1, nxt);
;         const char* nA = has_next ? (const char*)g.A + nxt.aoff : cA; const char* nB = has_next ? (const char*)g.Bt + nxt.boff : cB;
;     ...
; #pragma unroll
;         for (int a = 0; a < 2; ++a)
; #pragma unroll
;             for (int b = 0; b < 2; ++b)
; #pragma unroll
;                 for (int m = 0; m < 4; ++m)
; #pragma unroll
;                     for (int n = 0; n < 2; ++n) acc[a][b][m][n] = (f32x4){0.f, 0.f, 0.f, 0.f};
.LBB0_576:
	s_add_u32 s34, s43, s28
	s_addc_u32 s35, s55, s29
	s_and_b64 s[36:37], s[10:11], exec
	s_cselect_b32 s13, s35, s51
	s_cselect_b32 s33, s34, s50
	s_add_u32 s36, s56, s30
	s_addc_u32 s37, s57, s31
	s_and_b64 s[46:47], s[10:11], exec
	s_cselect_b32 s46, s37, s3
	s_cselect_b32 s47, s36, s2
	s_add_u32 s79, s2, 0x100
	s_addc_u32 s80, s3, 0
	s_add_u32 s2, s50, 0x40080
	v_mov_b32_e32 v0, 0
	s_addc_u32 s3, s51, 0
	s_mov_b32 s81, -2
	v_mov_b32_e32 v1, v0
	v_mov_b32_e32 v2, v0
	v_mov_b32_e32 v3, v0
	v_mov_b32_e32 v4, v0
	v_mov_b32_e32 v5, v0
	v_mov_b32_e32 v6, v0
	v_mov_b32_e32 v7, v0
	v_mov_b32_e32 v16, v0
	v_mov_b32_e32 v17, v0
	v_mov_b32_e32 v18, v0
	v_mov_b32_e32 v19, v0
	v_mov_b32_e32 v20, v0
	v_mov_b32_e32 v21, v0
	v_mov_b32_e32 v22, v0
	v_mov_b32_e32 v23, v0
	v_mov_b32_e32 v32, v0
	v_mov_b32_e32 v33, v0
	v_mov_b32_e32 v34, v0
	v_mov_b32_e32 v35, v0
	v_mov_b32_e32 v36, v0
	v_mov_b32_e32 v37, v0
	v_mov_b32_e32 v38, v0
	v_mov_b32_e32 v39, v0
	v_mov_b32_e32 v48, v0
	v_mov_b32_e32 v49, v0
	v_mov_b32_e32 v50, v0
	v_mov_b32_e32 v51, v0
	v_mov_b32_e32 v52, v0
	v_mov_b32_e32 v53, v0
	v_mov_b32_e32 v54, v0
	v_mov_b32_e32 v55, v0
	v_mov_b32_e32 v8, v0
	v_mov_b32_e32 v9, v0
	v_mov_b32_e32 v10, v0
	v_mov_b32_e32 v11, v0
	v_mov_b32_e32 v12, v0
	v_mov_b32_e32 v13, v0
	v_mov_b32_e32 v14, v0
	v_mov_b32_e32 v15, v0
	v_mov_b32_e32 v24, v0
	v_mov_b32_e32 v25, v0
	v_mov_b32_e32 v26, v0
	v_mov_b32_e32 v27, v0
	v_mov_b32_e32 v28, v0
	v_mov_b32_e32 v29, v0
	v_mov_b32_e32 v30, v0
	v_mov_b32_e32 v31, v0
	v_mov_b32_e32 v40, v0
	v_mov_b32_e32 v41, v0
	v_mov_b32_e32 v42, v0
	v_mov_b32_e32 v43, v0
	v_mov_b32_e32 v44, v0
	v_mov_b32_e32 v45, v0
	v_mov_b32_e32 v46, v0
	v_mov_b32_e32 v47, v0
	v_mov_b32_e32 v56, v0
	v_mov_b32_e32 v57, v0
	v_mov_b32_e32 v58, v0
	v_mov_b32_e32 v59, v0
	v_mov_b32_e32 v60, v0
	v_mov_b32_e32 v61, v0
	v_mov_b32_e32 v62, v0
	v_mov_b32_e32 v63, v0
	v_mov_b32_e32 v64, v0
	v_mov_b32_e32 v65, v0
	v_mov_b32_e32 v66, v0
	v_mov_b32_e32 v67, v0
	v_mov_b32_e32 v68, v0
	v_mov_b32_e32 v69, v0
	v_mov_b32_e32 v70, v0
	v_mov_b32_e32 v71, v0
	v_mov_b32_e32 v80, v0
	v_mov_b32_e32 v81, v0
	v_mov_b32_e32 v82, v0
	v_mov_b32_e32 v83, v0
	v_mov_b32_e32 v84, v0
	v_mov_b32_e32 v85, v0
	v_mov_b32_e32 v86, v0
	v_mov_b32_e32 v87, v0
	v_mov_b32_e32 v96, v0
	v_mov_b32_e32 v97, v0
	v_mov_b32_e32 v98, v0
	v_mov_b32_e32 v99, v0
	s_nop 0
	v_mov_b32_e32 v100, v0
	v_mov_b32_e32 v101, v0
	v_mov_b32_e32 v102, v0
	v_mov_b32_e32 v103, v0
	v_mov_b32_e32 v112, v0
	v_mov_b32_e32 v113, v0
	v_mov_b32_e32 v114, v0
	v_mov_b32_e32 v115, v0
	v_mov_b32_e32 v116, v0
	v_mov_b32_e32 v117, v0
	v_mov_b32_e32 v118, v0
	v_mov_b32_e32 v119, v0
	v_mov_b32_e32 v72, v0
	v_mov_b32_e32 v73, v0
	v_mov_b32_e32 v74, v0
	v_mov_b32_e32 v75, v0
	v_mov_b32_e32 v76, v0
	v_mov_b32_e32 v77, v0
	v_mov_b32_e32 v78, v0
	v_mov_b32_e32 v79, v0
	v_mov_b32_e32 v88, v0
	v_mov_b32_e32 v89, v0
	v_mov_b32_e32 v90, v0
	v_mov_b32_e32 v91, v0
	v_mov_b32_e32 v92, v0
	v_mov_b32_e32 v93, v0
	v_mov_b32_e32 v94, v0
	v_mov_b32_e32 v95, v0
	v_mov_b32_e32 v104, v0
	v_mov_b32_e32 v105, v0
	v_mov_b32_e32 v106, v0
	v_mov_b32_e32 v107, v0
	v_mov_b32_e32 v108, v0
	v_mov_b32_e32 v109, v0
	v_mov_b32_e32 v110, v0
	v_mov_b32_e32 v111, v0
	v_mov_b32_e32 v120, v0
	v_mov_b32_e32 v121, v0
	v_mov_b32_e32 v122, v0
	v_mov_b32_e32 v123, v0
	v_mov_b32_e32 v124, v0
	v_mov_b32_e32 v125, v0
	v_mov_b32_e32 v126, v0
	v_mov_b32_e32 v127, v0

; template <class Epi, class Sched>
; __device__ __forceinline__ void gemm_phase(PG8_LAS unsigned char* lds, PG8_LAS unsigned char* xl, const Gemm g, const Sched& S, const Epi& E) {
;     ...
;         const bool has_next = S.next(ui + 1, nxt);
;         const char* nA = has_next ? (const char*)g.A + nxt.aoff : cA; const char* nB = has_next ? (const char*)g.Bt + nxt.boff : cB;
;     ...
; #pragma unroll
;         for (int a = 0; a < 2; ++a)
; #pragma unroll
;             for (int b = 0; b < 2; ++b)
; #pragma unroll
;                 for (int m = 0; m < 4; ++m)
; #pragma unroll
;                     for (int n = 0; n < 2; ++n) acc[a][b][m][n] = (f32x4){0.f, 0.f, 0.f, 0.f};
.LBB0_724:
	s_add_u32 s26, s43, s20
	s_addc_u32 s27, s50, s21
	s_and_b64 s[28:29], s[8:9], exec
	s_cselect_b32 s33, s27, s35
	s_cselect_b32 s46, s26, s34
	s_add_u32 s28, s51, s22
	s_addc_u32 s29, s52, s23
	s_and_b64 s[36:37], s[8:9], exec
	s_cselect_b32 s47, s29, s31
	s_cselect_b32 s72, s28, s30
	s_add_u32 s73, s30, 0x100
	s_addc_u32 s74, s31, 0
	s_add_u32 s30, s34, 0x40080
	v_mov_b32_e32 v0, 0
	s_addc_u32 s31, s35, 0
	s_mov_b32 s75, -2
	s_waitcnt lgkmcnt(0)
	v_mov_b32_e32 v1, v0
	v_mov_b32_e32 v2, v0
	v_mov_b32_e32 v3, v0
	v_mov_b32_e32 v4, v0
	v_mov_b32_e32 v5, v0
	v_mov_b32_e32 v6, v0
	v_mov_b32_e32 v7, v0
	v_mov_b32_e32 v16, v0
	v_mov_b32_e32 v17, v0
	v_mov_b32_e32 v18, v0
	v_mov_b32_e32 v19, v0
	v_mov_b32_e32 v20, v0
	v_mov_b32_e32 v21, v0
	v_mov_b32_e32 v22, v0
	v_mov_b32_e32 v23, v0
	v_mov_b32_e32 v32, v0
	v_mov_b32_e32 v33, v0
	v_mov_b32_e32 v34, v0
	v_mov_b32_e32 v35, v0
	v_mov_b32_e32 v36, v0
	v_mov_b32_e32 v37, v0
	v_mov_b32_e32 v38, v0
	v_mov_b32_e32 v39, v0
	v_mov_b32_e32 v48, v0
	v_mov_b32_e32 v49, v0
	v_mov_b32_e32 v50, v0
	v_mov_b32_e32 v51, v0
	v_mov_b32_e32 v52, v0
	v_mov_b32_e32 v53, v0
	v_mov_b32_e32 v54, v0
	v_mov_b32_e32 v55, v0
	v_mov_b32_e32 v8, v0
	v_mov_b32_e32 v9, v0
	v_mov_b32_e32 v10, v0
	v_mov_b32_e32 v11, v0
	v_mov_b32_e32 v12, v0
	v_mov_b32_e32 v13, v0
	v_mov_b32_e32 v14, v0
	v_mov_b32_e32 v15, v0
	v_mov_b32_e32 v24, v0
	v_mov_b32_e32 v25, v0
	v_mov_b32_e32 v26, v0
	v_mov_b32_e32 v27, v0
	v_mov_b32_e32 v28, v0
	v_mov_b32_e32 v29, v0
	v_mov_b32_e32 v30, v0
	v_mov_b32_e32 v31, v0
	v_mov_b32_e32 v40, v0
	v_mov_b32_e32 v41, v0
	v_mov_b32_e32 v42, v0
	v_mov_b32_e32 v43, v0
	v_mov_b32_e32 v44, v0
	v_mov_b32_e32 v45, v0
	v_mov_b32_e32 v46, v0
	v_mov_b32_e32 v47, v0
	v_mov_b32_e32 v56, v0
	v_mov_b32_e32 v57, v0
	v_mov_b32_e32 v58, v0
	v_mov_b32_e32 v59, v0
	v_mov_b32_e32 v60, v0
	v_mov_b32_e32 v61, v0
	v_mov_b32_e32 v62, v0
	v_mov_b32_e32 v63, v0
	v_mov_b32_e32 v64, v0
	v_mov_b32_e32 v65, v0
	v_mov_b32_e32 v66, v0
	v_mov_b32_e32 v67, v0
	v_mov_b32_e32 v68, v0
	v_mov_b32_e32 v69, v0
	v_mov_b32_e32 v70, v0
	v_mov_b32_e32 v71, v0
	v_mov_b32_e32 v80, v0
	v_mov_b32_e32 v81, v0
	v_mov_b32_e32 v82, v0
	v_mov_b32_e32 v83, v0
	v_mov_b32_e32 v84, v0
	v_mov_b32_e32 v85, v0
	v_mov_b32_e32 v86, v0
	v_mov_b32_e32 v87, v0
	v_mov_b32_e32 v96, v0
	v_mov_b32_e32 v97, v0
	v_mov_b32_e32 v98, v0
	v_mov_b32_e32 v99, v0
	s_nop 0
	v_mov_b32_e32 v100, v0
	v_mov_b32_e32 v101, v0
	v_mov_b32_e32 v102, v0
	v_mov_b32_e32 v103, v0
	v_mov_b32_e32 v112, v0
	v_mov_b32_e32 v113, v0
	v_mov_b32_e32 v114, v0
	v_mov_b32_e32 v115, v0
	v_mov_b32_e32 v116, v0
	v_mov_b32_e32 v117, v0
	v_mov_b32_e32 v118, v0
	v_mov_b32_e32 v119, v0
	v_mov_b32_e32 v72, v0
	v_mov_b32_e32 v73, v0
	v_mov_b32_e32 v74, v0
	v_mov_b32_e32 v75, v0
	v_mov_b32_e32 v76, v0
	v_mov_b32_e32 v77, v0
	v_mov_b32_e32 v78, v0
	v_mov_b32_e32 v79, v0
	v_mov_b32_e32 v88, v0
	v_mov_b32_e32 v89, v0
	v_mov_b32_e32 v90, v0
	v_mov_b32_e32 v91, v0
	v_mov_b32_e32 v92, v0
	v_mov_b32_e32 v93, v0
	v_mov_b32_e32 v94, v0
	v_mov_b32_e32 v95, v0
	v_mov_b32_e32 v104, v0
	v_mov_b32_e32 v105, v0
	v_mov_b32_e32 v106, v0
	v_mov_b32_e32 v107, v0
	v_mov_b32_e32 v108, v0
	v_mov_b32_e32 v109, v0
	v_mov_b32_e32 v110, v0
	v_mov_b32_e32 v111, v0
	v_mov_b32_e32 v120, v0
	v_mov_b32_e32 v121, v0
	v_mov_b32_e32 v122, v0
	v_mov_b32_e32 v123, v0
	v_mov_b32_e32 v124, v0
	v_mov_b32_e32 v125, v0
	v_mov_b32_e32 v126, v0
	v_mov_b32_e32 v127, v0

; template <class Epi, class Sched>
; __device__ __forceinline__ void gemm_phase(PG8_LAS unsigned char* lds, PG8_LAS unsigned char* xl, const Gemm g, const Sched& S, const Epi& E) {
;     ...
;         const bool has_next = S.next(ui + 1, nxt);
;         const char* nA = has_next ? (const char*)g.A + nxt.aoff : cA; const char* nB = has_next ? (const char*)g.Bt + nxt.boff : cB;
;     ...
; #pragma unroll
;         for (int a = 0; a < 2; ++a)
; #pragma unroll
;             for (int b = 0; b < 2; ++b)
; #pragma unroll
;                 for (int m = 0; m < 4; ++m)
; #pragma unroll
;                     for (int n = 0; n < 2; ++n) acc[a][b][m][n] = (f32x4){0.f, 0.f, 0.f, 0.f};
.LBB0_824:
	s_add_u32 s26, s37, s20
	s_addc_u32 s27, s42, s21
	s_and_b64 s[28:29], s[6:7], exec
	s_cselect_b32 s46, s27, s31
	s_cselect_b32 s47, s26, s30
	s_add_u32 s28, s43, s22
	s_addc_u32 s29, s50, s23
	s_and_b64 s[34:35], s[6:7], exec
	s_cselect_b32 s70, s29, s3
	s_cselect_b32 s72, s28, s2
	s_add_u32 s73, s2, 0x100
	s_addc_u32 s74, s3, 0
	s_add_u32 s2, s30, 0x40080
	v_mov_b32_e32 v0, 0
	s_addc_u32 s3, s31, 0
	s_mov_b32 s75, -2
	v_mov_b32_e32 v1, v0
	v_mov_b32_e32 v2, v0
	v_mov_b32_e32 v3, v0
	v_mov_b32_e32 v8, v0
	v_mov_b32_e32 v9, v0
	v_mov_b32_e32 v10, v0
	v_mov_b32_e32 v11, v0
	v_mov_b32_e32 v16, v0
	v_mov_b32_e32 v17, v0
	v_mov_b32_e32 v18, v0
	v_mov_b32_e32 v19, v0
	v_mov_b32_e32 v24, v0
	v_mov_b32_e32 v25, v0
	v_mov_b32_e32 v26, v0
	v_mov_b32_e32 v27, v0
	v_mov_b32_e32 v32, v0
	v_mov_b32_e32 v33, v0
	v_mov_b32_e32 v34, v0
	v_mov_b32_e32 v35, v0
	v_mov_b32_e32 v40, v0
	v_mov_b32_e32 v41, v0
	v_mov_b32_e32 v42, v0
	v_mov_b32_e32 v43, v0
	v_mov_b32_e32 v48, v0
	v_mov_b32_e32 v49, v0
	v_mov_b32_e32 v50, v0
	v_mov_b32_e32 v51, v0
	v_mov_b32_e32 v56, v0
	v_mov_b32_e32 v57, v0
	v_mov_b32_e32 v58, v0
	v_mov_b32_e32 v59, v0
	v_mov_b32_e32 v4, v0
	v_mov_b32_e32 v5, v0
	v_mov_b32_e32 v6, v0
	v_mov_b32_e32 v7, v0
	v_mov_b32_e32 v12, v0
	v_mov_b32_e32 v13, v0
	v_mov_b32_e32 v14, v0
	v_mov_b32_e32 v15, v0
	v_mov_b32_e32 v20, v0
	v_mov_b32_e32 v21, v0
	v_mov_b32_e32 v22, v0
	v_mov_b32_e32 v23, v0
	v_mov_b32_e32 v28, v0
	v_mov_b32_e32 v29, v0
	v_mov_b32_e32 v30, v0
	v_mov_b32_e32 v31, v0
	v_mov_b32_e32 v36, v0
	v_mov_b32_e32 v37, v0
	v_mov_b32_e32 v38, v0
	v_mov_b32_e32 v39, v0
	v_mov_b32_e32 v44, v0
	v_mov_b32_e32 v45, v0
	v_mov_b32_e32 v46, v0
	v_mov_b32_e32 v47, v0
	v_mov_b32_e32 v52, v0
	v_mov_b32_e32 v53, v0
	v_mov_b32_e32 v54, v0
	v_mov_b32_e32 v55, v0
	v_mov_b32_e32 v60, v0
	v_mov_b32_e32 v61, v0
	v_mov_b32_e32 v62, v0
	v_mov_b32_e32 v63, v0
	v_mov_b32_e32 v64, v0
	v_mov_b32_e32 v65, v0
	v_mov_b32_e32 v66, v0
	v_mov_b32_e32 v67, v0
	v_mov_b32_e32 v72, v0
	v_mov_b32_e32 v73, v0
	v_mov_b32_e32 v74, v0
	v_mov_b32_e32 v75, v0
	v_mov_b32_e32 v80, v0
	v_mov_b32_e32 v81, v0
	v_mov_b32_e32 v82, v0
	v_mov_b32_e32 v83, v0
	v_mov_b32_e32 v88, v0
	v_mov_b32_e32 v89, v0
	v_mov_b32_e32 v90, v0
	v_mov_b32_e32 v91, v0
	v_mov_b32_e32 v96, v0
	v_mov_b32_e32 v97, v0
	v_mov_b32_e32 v98, v0
	v_mov_b32_e32 v99, v0
	s_nop 0
	v_mov_b32_e32 v104, v0
	v_mov_b32_e32 v105, v0
	v_mov_b32_e32 v106, v0
	v_mov_b32_e32 v107, v0
	v_mov_b32_e32 v112, v0
	v_mov_b32_e32 v113, v0
	v_mov_b32_e32 v114, v0
	v_mov_b32_e32 v115, v0
	v_mov_b32_e32 v120, v0
	v_mov_b32_e32 v121, v0
	v_mov_b32_e32 v122, v0
	v_mov_b32_e32 v123, v0
	v_mov_b32_e32 v68, v0
	v_mov_b32_e32 v69, v0
	v_mov_b32_e32 v70, v0
	v_mov_b32_e32 v71, v0
	v_mov_b32_e32 v76, v0
	v_mov_b32_e32 v77, v0
	v_mov_b32_e32 v78, v0
	v_mov_b32_e32 v79, v0
	v_mov_b32_e32 v84, v0
	v_mov_b32_e32 v85, v0
	v_mov_b32_e32 v86, v0
	v_mov_b32_e32 v87, v0
	v_mov_b32_e32 v92, v0
	v_mov_b32_e32 v93, v0
	v_mov_b32_e32 v94, v0
	v_mov_b32_e32 v95, v0
	v_mov_b32_e32 v100, v0
	v_mov_b32_e32 v101, v0
	v_mov_b32_e32 v102, v0
	v_mov_b32_e32 v103, v0
	v_mov_b32_e32 v108, v0
	v_mov_b32_e32 v109, v0
	v_mov_b32_e32 v110, v0
	v_mov_b32_e32 v111, v0
	v_mov_b32_e32 v116, v0
	v_mov_b32_e32 v117, v0
	v_mov_b32_e32 v118, v0
	v_mov_b32_e32 v119, v0
	v_mov_b32_e32 v124, v0
	v_mov_b32_e32 v125, v0
	v_mov_b32_e32 v126, v0
	v_mov_b32_e32 v127, v0

; template <class Epi, class Sched>
; __device__ __forceinline__ void gemm_phase(PG8_LAS unsigned char* lds, PG8_LAS unsigned char* xl, const Gemm g, const Sched& S, const Epi& E) {
;     ...
;         const bool has_next = S.next(ui + 1, nxt);
;         const char* nA = has_next ? (const char*)g.A + nxt.aoff : cA; const char* nB = has_next ? (const char*)g.Bt + nxt.boff : cB;
;     ...
; #pragma unroll
;         for (int a = 0; a < 2; ++a)
; #pragma unroll
;             for (int b = 0; b < 2; ++b)
; #pragma unroll
;                 for (int m = 0; m < 4; ++m)
; #pragma unroll
;                     for (int n = 0; n < 2; ++n) acc[a][b][m][n] = (f32x4){0.f, 0.f, 0.f, 0.f};
.LBB0_913:
	s_add_u32 s20, s55, s16
	s_addc_u32 s21, s56, s17
	s_and_b64 s[22:23], s[6:7], exec
	s_cselect_b32 s61, s21, s27
	s_cselect_b32 s62, s20, s26
	s_add_u32 s22, s57, s18
	s_addc_u32 s23, s58, s19
	s_and_b64 s[30:31], s[6:7], exec
	s_cselect_b32 s63, s23, s29
	s_cselect_b32 s64, s22, s28
	s_add_u32 s65, s28, 0x100
	v_mov_b32_e32 v0, 0
	s_addc_u32 s66, s29, 0
	s_mov_b32 s67, -2
	v_mov_b32_e32 v1, v0
	v_mov_b32_e32 v2, v0
	v_mov_b32_e32 v3, v0
	v_mov_b32_e32 v4, v0
	v_mov_b32_e32 v5, v0
	v_mov_b32_e32 v6, v0
	v_mov_b32_e32 v7, v0
	v_mov_b32_e32 v16, v0
	v_mov_b32_e32 v17, v0
	v_mov_b32_e32 v18, v0
	v_mov_b32_e32 v19, v0
	v_mov_b32_e32 v20, v0
	v_mov_b32_e32 v21, v0
	v_mov_b32_e32 v22, v0
	v_mov_b32_e32 v23, v0
	v_mov_b32_e32 v32, v0
	v_mov_b32_e32 v33, v0
	v_mov_b32_e32 v34, v0
	v_mov_b32_e32 v35, v0
	v_mov_b32_e32 v36, v0
	v_mov_b32_e32 v37, v0
	v_mov_b32_e32 v38, v0
	v_mov_b32_e32 v39, v0
	v_mov_b32_e32 v48, v0
	v_mov_b32_e32 v49, v0
	v_mov_b32_e32 v50, v0
	v_mov_b32_e32 v51, v0
	v_mov_b32_e32 v52, v0
	v_mov_b32_e32 v53, v0
	v_mov_b32_e32 v54, v0
	v_mov_b32_e32 v55, v0
	v_mov_b32_e32 v8, v0
	v_mov_b32_e32 v9, v0
	v_mov_b32_e32 v10, v0
	v_mov_b32_e32 v11, v0
	v_mov_b32_e32 v12, v0
	v_mov_b32_e32 v13, v0
	v_mov_b32_e32 v14, v0
	v_mov_b32_e32 v15, v0
	v_mov_b32_e32 v24, v0
	v_mov_b32_e32 v25, v0
	v_mov_b32_e32 v26, v0
	v_mov_b32_e32 v27, v0
	v_mov_b32_e32 v28, v0
	v_mov_b32_e32 v29, v0
	v_mov_b32_e32 v30, v0
	v_mov_b32_e32 v31, v0
	v_mov_b32_e32 v40, v0
	v_mov_b32_e32 v41, v0
	v_mov_b32_e32 v42, v0
	v_mov_b32_e32 v43, v0
	v_mov_b32_e32 v44, v0
	v_mov_b32_e32 v45, v0
	v_mov_b32_e32 v46, v0
	v_mov_b32_e32 v47, v0
	v_mov_b32_e32 v56, v0
	v_mov_b32_e32 v57, v0
	v_mov_b32_e32 v58, v0
	v_mov_b32_e32 v59, v0
	v_mov_b32_e32 v60, v0
	v_mov_b32_e32 v61, v0
	v_mov_b32_e32 v62, v0
	v_mov_b32_e32 v63, v0
	v_mov_b32_e32 v64, v0
	v_mov_b32_e32 v65, v0
	v_mov_b32_e32 v66, v0
	v_mov_b32_e32 v67, v0
	v_mov_b32_e32 v68, v0
	v_mov_b32_e32 v69, v0
	v_mov_b32_e32 v70, v0
	v_mov_b32_e32 v71, v0
	v_mov_b32_e32 v80, v0
	v_mov_b32_e32 v81, v0
	v_mov_b32_e32 v82, v0
	v_mov_b32_e32 v83, v0
	v_mov_b32_e32 v84, v0
	v_mov_b32_e32 v85, v0
	v_mov_b32_e32 v86, v0
	v_mov_b32_e32 v87, v0
	v_mov_b32_e32 v96, v0
	v_mov_b32_e32 v97, v0
	v_mov_b32_e32 v98, v0
	v_mov_b32_e32 v99, v0
	s_nop 0
	v_mov_b32_e32 v100, v0
	v_mov_b32_e32 v101, v0
	v_mov_b32_e32 v102, v0
	v_mov_b32_e32 v103, v0
	v_mov_b32_e32 v112, v0
	v_mov_b32_e32 v113, v0
	v_mov_b32_e32 v114, v0
	v_mov_b32_e32 v115, v0
	v_mov_b32_e32 v116, v0
	v_mov_b32_e32 v117, v0
	v_mov_b32_e32 v118, v0
	v_mov_b32_e32 v119, v0
	v_mov_b32_e32 v72, v0
	v_mov_b32_e32 v73, v0
	v_mov_b32_e32 v74, v0
	v_mov_b32_e32 v75, v0
	v_mov_b32_e32 v76, v0
	v_mov_b32_e32 v77, v0
	v_mov_b32_e32 v78, v0
	v_mov_b32_e32 v79, v0
	v_mov_b32_e32 v88, v0
	v_mov_b32_e32 v89, v0
	v_mov_b32_e32 v90, v0
	v_mov_b32_e32 v91, v0
	v_mov_b32_e32 v92, v0
	v_mov_b32_e32 v93, v0
	v_mov_b32_e32 v94, v0
	v_mov_b32_e32 v95, v0
	v_mov_b32_e32 v104, v0
	v_mov_b32_e32 v105, v0
	v_mov_b32_e32 v106, v0
	v_mov_b32_e32 v107, v0
	v_mov_b32_e32 v108, v0
	v_mov_b32_e32 v109, v0
	v_mov_b32_e32 v110, v0
	v_mov_b32_e32 v111, v0
	v_mov_b32_e32 v120, v0
	v_mov_b32_e32 v121, v0
	v_mov_b32_e32 v122, v0
	v_mov_b32_e32 v123, v0
	v_mov_b32_e32 v124, v0
	v_mov_b32_e32 v125, v0
	v_mov_b32_e32 v126, v0
	v_mov_b32_e32 v127, v0

; template <class Epi, class Sched>
; __device__ __forceinline__ void gemm_phase(PG8_LAS unsigned char* lds, PG8_LAS unsigned char* xl, const Gemm g, const Sched& S, const Epi& E) {
;     ...
;         const bool has_next = S.next(ui + 1, nxt);
;         const char* nA = has_next ? (const char*)g.A + nxt.aoff : cA; const char* nB = has_next ? (const char*)g.Bt + nxt.boff : cB;
;     ...
; #pragma unroll
;         for (int a = 0; a < 2; ++a)
; #pragma unroll
;             for (int b = 0; b < 2; ++b)
; #pragma unroll
;                 for (int m = 0; m < 4; ++m)
; #pragma unroll
;                     for (int n = 0; n < 2; ++n) acc[a][b][m][n] = (f32x4){0.f, 0.f, 0.f, 0.f};
.LBB0_941:
	s_add_u32 s34, s55, s28
	s_addc_u32 s35, s56, s29
	s_and_b64 s[36:37], s[10:11], exec
	s_cselect_b32 s33, s35, s3
	s_cselect_b32 s46, s34, s2
	s_add_u32 s36, s57, s30
	s_addc_u32 s37, s58, s31
	s_and_b64 s[50:51], s[10:11], exec
	s_cselect_b32 s47, s37, s49
	s_cselect_b32 s77, s36, s48
	s_add_u32 s78, s48, 0x100
	v_mov_b32_e32 v0, 0
	s_addc_u32 s79, s49, 0
	s_mov_b32 s80, -2
	v_mov_b32_e32 v1, v0
	v_mov_b32_e32 v2, v0
	v_mov_b32_e32 v3, v0
	v_mov_b32_e32 v4, v0
	v_mov_b32_e32 v5, v0
	v_mov_b32_e32 v6, v0
	v_mov_b32_e32 v7, v0
	v_mov_b32_e32 v16, v0
	v_mov_b32_e32 v17, v0
	v_mov_b32_e32 v18, v0
	v_mov_b32_e32 v19, v0
	v_mov_b32_e32 v20, v0
	v_mov_b32_e32 v21, v0
	v_mov_b32_e32 v22, v0
	v_mov_b32_e32 v23, v0
	v_mov_b32_e32 v32, v0
	v_mov_b32_e32 v33, v0
	v_mov_b32_e32 v34, v0
	v_mov_b32_e32 v35, v0
	v_mov_b32_e32 v36, v0
	v_mov_b32_e32 v37, v0
	v_mov_b32_e32 v38, v0
	v_mov_b32_e32 v39, v0
	v_mov_b32_e32 v48, v0
	v_mov_b32_e32 v49, v0
	v_mov_b32_e32 v50, v0
	v_mov_b32_e32 v51, v0
	v_mov_b32_e32 v52, v0
	v_mov_b32_e32 v53, v0
	v_mov_b32_e32 v54, v0
	v_mov_b32_e32 v55, v0
	v_mov_b32_e32 v8, v0
	v_mov_b32_e32 v9, v0
	v_mov_b32_e32 v10, v0
	v_mov_b32_e32 v11, v0
	v_mov_b32_e32 v12, v0
	v_mov_b32_e32 v13, v0
	v_mov_b32_e32 v14, v0
	v_mov_b32_e32 v15, v0
	v_mov_b32_e32 v24, v0
	v_mov_b32_e32 v25, v0
	v_mov_b32_e32 v26, v0
	v_mov_b32_e32 v27, v0
	v_mov_b32_e32 v28, v0
	v_mov_b32_e32 v29, v0
	v_mov_b32_e32 v30, v0
	v_mov_b32_e32 v31, v0
	v_mov_b32_e32 v40, v0
	v_mov_b32_e32 v41, v0
	v_mov_b32_e32 v42, v0
	v_mov_b32_e32 v43, v0
	v_mov_b32_e32 v44, v0
	v_mov_b32_e32 v45, v0
	v_mov_b32_e32 v46, v0
	v_mov_b32_e32 v47, v0
	v_mov_b32_e32 v56, v0
	v_mov_b32_e32 v57, v0
	v_mov_b32_e32 v58, v0
	v_mov_b32_e32 v59, v0
	v_mov_b32_e32 v60, v0
	v_mov_b32_e32 v61, v0
	v_mov_b32_e32 v62, v0
	v_mov_b32_e32 v63, v0
	v_mov_b32_e32 v64, v0
	v_mov_b32_e32 v65, v0
	v_mov_b32_e32 v66, v0
	v_mov_b32_e32 v67, v0
	v_mov_b32_e32 v68, v0
	v_mov_b32_e32 v69, v0
	v_mov_b32_e32 v70, v0
	v_mov_b32_e32 v71, v0
	v_mov_b32_e32 v80, v0
	v_mov_b32_e32 v81, v0
	v_mov_b32_e32 v82, v0
	v_mov_b32_e32 v83, v0
	v_mov_b32_e32 v84, v0
	v_mov_b32_e32 v85, v0
	v_mov_b32_e32 v86, v0
	v_mov_b32_e32 v87, v0
	v_mov_b32_e32 v96, v0
	v_mov_b32_e32 v97, v0
	v_mov_b32_e32 v98, v0
	v_mov_b32_e32 v99, v0
	s_nop 0
	v_mov_b32_e32 v100, v0
	v_mov_b32_e32 v101, v0
	v_mov_b32_e32 v102, v0
	v_mov_b32_e32 v103, v0
	v_mov_b32_e32 v112, v0
	v_mov_b32_e32 v113, v0
	v_mov_b32_e32 v114, v0
	v_mov_b32_e32 v115, v0
	v_mov_b32_e32 v116, v0
	v_mov_b32_e32 v117, v0
	v_mov_b32_e32 v118, v0
	v_mov_b32_e32 v119, v0
	v_mov_b32_e32 v72, v0
	v_mov_b32_e32 v73, v0
	v_mov_b32_e32 v74, v0
	v_mov_b32_e32 v75, v0
	v_mov_b32_e32 v76, v0
	v_mov_b32_e32 v77, v0
	v_mov_b32_e32 v78, v0
	v_mov_b32_e32 v79, v0
	v_mov_b32_e32 v88, v0
	v_mov_b32_e32 v89, v0
	v_mov_b32_e32 v90, v0
	v_mov_b32_e32 v91, v0
	v_mov_b32_e32 v92, v0
	v_mov_b32_e32 v93, v0
	v_mov_b32_e32 v94, v0
	v_mov_b32_e32 v95, v0
	v_mov_b32_e32 v104, v0
	v_mov_b32_e32 v105, v0
	v_mov_b32_e32 v106, v0
	v_mov_b32_e32 v107, v0
	v_mov_b32_e32 v108, v0
	v_mov_b32_e32 v109, v0
	v_mov_b32_e32 v110, v0
	v_mov_b32_e32 v111, v0
	v_mov_b32_e32 v120, v0
	v_mov_b32_e32 v121, v0
	v_mov_b32_e32 v122, v0
	v_mov_b32_e32 v123, v0
	v_mov_b32_e32 v124, v0
	v_mov_b32_e32 v125, v0
	v_mov_b32_e32 v126, v0
	v_mov_b32_e32 v127, v0
